# final RMSNorm phase: norm weights kept in registers for the four elements of a trip (three reloads and vmcnt(0) drains per trip removed)
# speedup vs baseline: 1.0012x; 1.0012x over previous
.LBB0_841:
	v_lshrrev_b64 v[2:3], 6, v[0:1]
	v_and_b32_e32 v3, 0x3ffffff, v3
	v_and_b32_e32 v2, -4, v2
	v_lshl_add_u64 v[18:19], v[0:1], 0, s[8:9]
	v_lshl_add_u64 v[2:3], s[38:39], 0, v[2:3]
	v_cmp_gt_u64_e64 s[2:3], s[6:7], v[18:19]
	global_load_dword v34, v[2:3], off
	v_lshl_add_u64 v[20:21], s[30:31], 0, v[14:15]
	v_cndmask_b32_e64 v3, v1, v19, s[2:3]
	v_cndmask_b32_e64 v2, v0, v18, s[2:3]
	v_lshl_add_u64 v[4:5], v[2:3], 4, s[30:31]
	v_lshrrev_b64 v[2:3], 6, v[2:3]
	v_and_b32_e32 v3, 0x3ffffff, v3
	v_and_b32_e32 v2, -4, v2
	v_lshl_add_u64 v[2:3], s[38:39], 0, v[2:3]
	global_load_dword v25, v[2:3], off
	v_lshl_add_u64 v[2:3], s[12:13], 0, v[0:1]
	v_cmp_gt_u64_e64 s[0:1], s[6:7], v[2:3]
	global_load_dwordx4 v[26:29], v[20:21], off
	global_load_dwordx4 v[8:11], v[4:5], off
	v_cndmask_b32_e64 v3, v1, v3, s[0:1]
	v_cndmask_b32_e64 v2, v0, v2, s[0:1]
	v_lshl_add_u64 v[4:5], v[2:3], 4, s[30:31]
	v_lshrrev_b64 v[2:3], 6, v[2:3]
	v_and_b32_e32 v3, 0x3ffffff, v3
	v_and_b32_e32 v2, -4, v2
	v_lshl_add_u64 v[2:3], s[38:39], 0, v[2:3]
	global_load_dword v24, v[2:3], off
	v_lshl_add_u64 v[2:3], s[20:21], 0, v[0:1]
	v_cmp_gt_u64_e32 vcc, s[6:7], v[2:3]
	v_and_b32_e32 v16, 0x3fc, v12
	global_load_dwordx4 v[4:7], v[4:5], off
	v_cndmask_b32_e32 v31, v1, v3, vcc
	v_cndmask_b32_e32 v30, v0, v2, vcc
	v_lshl_add_u64 v[0:1], v[30:31], 4, s[30:31]
	v_lshrrev_b64 v[30:31], 6, v[30:31]
	v_and_b32_e32 v31, 0x3ffffff, v31
	v_and_b32_e32 v30, -4, v30
	v_lshl_add_u64 v[30:31], s[38:39], 0, v[30:31]
	global_load_dwordx4 v[0:3], v[0:1], off
	v_lshlrev_b32_e32 v16, 2, v16
	global_load_dword v23, v[30:31], off
	global_load_dwordx4 v[30:33], v16, s[28:29]
	s_waitcnt vmcnt(8)
	v_fmamk_f32 v34, v34, 0x3a800000, v22
	v_mul_f32_e32 v35, 0x4b800000, v34
	v_cmp_gt_f32_e64 s[4:5], s33, v34
	s_nop 1
	v_cndmask_b32_e64 v34, v34, v35, s[4:5]
	v_rsq_f32_e32 v34, v34
	s_nop 0
	v_mul_f32_e32 v35, 0x45800000, v34
	v_cndmask_b32_e64 v34, v34, v35, s[4:5]
	s_waitcnt vmcnt(0)
	v_pk_mul_f32 v[38:39], v[34:35], v[32:33] op_sel_hi:[0,1]
	v_pk_mul_f32 v[36:37], v[34:35], v[30:31] op_sel_hi:[0,1]
	v_pk_mul_f32 v[26:27], v[26:27], v[36:37]
	v_pk_mul_f32 v[28:29], v[28:29], v[38:39]
	global_store_dwordx4 v[20:21], v[26:29], off
	s_and_saveexec_b64 s[4:5], s[2:3]
	s_cbranch_execz .LBB0_840
	v_fmamk_f32 v16, v25, 0x3a800000, v22
	v_mul_f32_e32 v25, 0x4b800000, v16
	v_cmp_gt_f32_e64 s[2:3], s33, v16
	s_nop 1
	v_cndmask_b32_e64 v16, v16, v25, s[2:3]
	v_rsq_f32_e32 v16, v16
	s_nop 0
	v_mul_f32_e32 v25, 0x45800000, v16
	v_cndmask_b32_e64 v16, v16, v25, s[2:3]
	v_pk_mul_f32 v[26:27], v[16:17], v[30:31] op_sel_hi:[0,1]
	v_pk_mul_f32 v[28:29], v[16:17], v[32:33] op_sel_hi:[0,1]
	v_pk_mul_f32 v[10:11], v[10:11], v[28:29]
	v_pk_mul_f32 v[8:9], v[8:9], v[26:27]
	v_lshl_add_u64 v[26:27], s[22:23], 0, v[14:15]
	global_store_dwordx4 v[26:27], v[8:11], off
	s_and_b64 exec, exec, s[0:1]
	s_cbranch_execz .LBB0_840
	v_fmamk_f32 v16, v24, 0x3a800000, v22
	v_mul_f32_e32 v24, 0x4b800000, v16
	v_cmp_gt_f32_e64 s[0:1], s33, v16
	s_nop 1
	v_cndmask_b32_e64 v16, v16, v24, s[0:1]
	v_rsq_f32_e32 v16, v16
	s_nop 0
	v_mul_f32_e32 v24, 0x45800000, v16
	v_cndmask_b32_e64 v16, v16, v24, s[0:1]
	v_pk_mul_f32 v[8:9], v[16:17], v[30:31] op_sel_hi:[0,1]
	v_pk_mul_f32 v[10:11], v[16:17], v[32:33] op_sel_hi:[0,1]
	v_pk_mul_f32 v[6:7], v[6:7], v[10:11]
	v_pk_mul_f32 v[4:5], v[4:5], v[8:9]
	v_lshl_add_u64 v[8:9], s[14:15], 0, v[14:15]
	global_store_dwordx4 v[8:9], v[4:7], off
	s_and_b64 exec, exec, vcc
	s_cbranch_execz .LBB0_840
	v_fmamk_f32 v8, v23, 0x3a800000, v22
	v_mul_f32_e32 v9, 0x4b800000, v8
	v_cmp_gt_f32_e32 vcc, s33, v8
	s_nop 1
	v_cndmask_b32_e32 v8, v8, v9, vcc
	v_rsq_f32_e32 v8, v8
	s_nop 0
	v_mul_f32_e32 v9, 0x45800000, v8
	v_cndmask_b32_e32 v8, v8, v9, vcc
	v_pk_mul_f32 v[4:5], v[8:9], v[30:31] op_sel_hi:[0,1]
	v_pk_mul_f32 v[6:7], v[8:9], v[32:33] op_sel_hi:[0,1]
	v_pk_mul_f32 v[2:3], v[2:3], v[6:7]
	v_pk_mul_f32 v[0:1], v[0:1], v[4:5]
	v_lshl_add_u64 v[4:5], s[18:19], 0, v[14:15]
	global_store_dwordx4 v[4:5], v[0:3], off
	s_branch .LBB0_840
